# cross-attention epilogue: v_permlane32_swap pairs adjacent 8-byte groups, 8 dwordx4 stores per lane instead of 16 dwordx2 (store widening)
# speedup vs baseline: 1.0074x; 1.0074x over previous
; __device__ __forceinline__ void xattn_phase(const bf16* QXB, const bf16* MKF, const bf16* MVF, bf16* OXB, int G, int tid) {
;     ...
;         const float inv = 1.0f / l_run; bf16* op = OXB + (row0 + r32) * XW + h * XHD;
; #pragma unroll
;         for (int dt = 0; dt < 4; ++dt)
; #pragma unroll
;             for (int g4 = 0; g4 < 4; ++g4) { u32x2_t w; w.x = cvtpk(o[dt][4 * g4 + 0] * inv, o[dt][4 * g4 + 1] * inv); w.y = cvtpk(o[dt][4 * g4 + 2] * inv, o[dt][4 * g4 + 3] * inv);
;                 *(u32x2_t*)(op + 32 * dt + 8 * g4 + 4 * hh) = w; }
.LBB0_1510:
	v_div_scale_f32 v66, s[2:3], v231, v231, 1.0
	v_rcp_f32_e32 v67, v66
	v_div_scale_f32 v68, vcc, 1.0, v231, 1.0
	s_add_i32 s8, s8, s70
	v_fma_f32 v69, -v66, v67, 1.0
	v_fmac_f32_e32 v67, v69, v67
	v_mul_f32_e32 v69, v68, v67
	v_fma_f32 v70, -v66, v69, v68
	v_fmac_f32_e32 v69, v70, v67
	v_fma_f32 v66, -v66, v69, v68
	v_div_fmas_f32 v66, v66, v67, v69
	v_div_fixup_f32 v66, v66, v231, 1.0
	v_lshl_add_u64 v[68:69], v[232:233], 1, s[16:17]
	v_lshl_add_u64 v[68:69], s[0:1], 1, v[68:69]
	v_mov_b32_e32 v231, v215
	v_lshl_add_u64 v[68:69], v[68:69], 0, v[230:231]
	v_lshl_add_u64 v[68:69], v[68:69], 0, v[230:231]
	v_pk_mul_f32 v[50:51], v[66:67], v[50:51] op_sel_hi:[0,1]
	v_pk_mul_f32 v[52:53], v[66:67], v[52:53] op_sel_hi:[0,1]
	v_pk_mul_f32 v[54:55], v[66:67], v[54:55] op_sel_hi:[0,1]
	v_pk_mul_f32 v[56:57], v[66:67], v[56:57] op_sel_hi:[0,1]
	v_pk_mul_f32 v[58:59], v[66:67], v[58:59] op_sel_hi:[0,1]
	v_pk_mul_f32 v[60:61], v[66:67], v[60:61] op_sel_hi:[0,1]
	v_pk_mul_f32 v[62:63], v[66:67], v[62:63] op_sel_hi:[0,1]
	v_pk_mul_f32 v[64:65], v[66:67], v[64:65] op_sel_hi:[0,1]
	v_cvt_pk_bf16_f32 v50, v50, v51
	v_cvt_pk_bf16_f32 v51, v52, v53
	v_cvt_pk_bf16_f32 v52, v54, v55
	v_cvt_pk_bf16_f32 v53, v56, v57
	v_cvt_pk_bf16_f32 v54, v58, v59
	v_cvt_pk_bf16_f32 v55, v60, v61
	v_cvt_pk_bf16_f32 v56, v62, v63
	v_cvt_pk_bf16_f32 v57, v64, v65
	s_nop 1
	v_permlane32_swap_b32_e32 v50, v52
	v_permlane32_swap_b32_e32 v51, v53
	v_permlane32_swap_b32_e32 v54, v56
	v_permlane32_swap_b32_e32 v55, v57
	global_store_dwordx4 v[68:69], v[50:53], off
	global_store_dwordx4 v[68:69], v[54:57], off offset:32
	v_pk_mul_f32 v[34:35], v[66:67], v[34:35] op_sel_hi:[0,1]
	v_pk_mul_f32 v[36:37], v[66:67], v[36:37] op_sel_hi:[0,1]
	v_pk_mul_f32 v[38:39], v[66:67], v[38:39] op_sel_hi:[0,1]
	v_pk_mul_f32 v[40:41], v[66:67], v[40:41] op_sel_hi:[0,1]
	v_pk_mul_f32 v[42:43], v[66:67], v[42:43] op_sel_hi:[0,1]
	v_pk_mul_f32 v[44:45], v[66:67], v[44:45] op_sel_hi:[0,1]
	v_pk_mul_f32 v[46:47], v[66:67], v[46:47] op_sel_hi:[0,1]
	v_pk_mul_f32 v[48:49], v[66:67], v[48:49] op_sel_hi:[0,1]
	v_cvt_pk_bf16_f32 v34, v34, v35
	v_cvt_pk_bf16_f32 v35, v36, v37
	v_cvt_pk_bf16_f32 v36, v38, v39
	v_cvt_pk_bf16_f32 v37, v40, v41
	v_cvt_pk_bf16_f32 v38, v42, v43
	v_cvt_pk_bf16_f32 v39, v44, v45
	v_cvt_pk_bf16_f32 v40, v46, v47
	v_cvt_pk_bf16_f32 v41, v48, v49
	s_nop 1
	v_permlane32_swap_b32_e32 v34, v36
	v_permlane32_swap_b32_e32 v35, v37
	v_permlane32_swap_b32_e32 v38, v40
	v_permlane32_swap_b32_e32 v39, v41
	global_store_dwordx4 v[68:69], v[34:37], off offset:64
	global_store_dwordx4 v[68:69], v[38:41], off offset:96
	v_pk_mul_f32 v[18:19], v[66:67], v[18:19] op_sel_hi:[0,1]
	v_pk_mul_f32 v[20:21], v[66:67], v[20:21] op_sel_hi:[0,1]
	v_pk_mul_f32 v[22:23], v[66:67], v[22:23] op_sel_hi:[0,1]
	v_pk_mul_f32 v[24:25], v[66:67], v[24:25] op_sel_hi:[0,1]
	v_pk_mul_f32 v[26:27], v[66:67], v[26:27] op_sel_hi:[0,1]
	v_pk_mul_f32 v[28:29], v[66:67], v[28:29] op_sel_hi:[0,1]
	v_pk_mul_f32 v[30:31], v[66:67], v[30:31] op_sel_hi:[0,1]
	v_pk_mul_f32 v[32:33], v[66:67], v[32:33] op_sel_hi:[0,1]
	v_cvt_pk_bf16_f32 v18, v18, v19
	v_cvt_pk_bf16_f32 v19, v20, v21
	v_cvt_pk_bf16_f32 v20, v22, v23
	v_cvt_pk_bf16_f32 v21, v24, v25
	v_cvt_pk_bf16_f32 v22, v26, v27
	v_cvt_pk_bf16_f32 v23, v28, v29
	v_cvt_pk_bf16_f32 v24, v30, v31
	v_cvt_pk_bf16_f32 v25, v32, v33
	s_nop 1
	v_permlane32_swap_b32_e32 v18, v20
	v_permlane32_swap_b32_e32 v19, v21
	v_permlane32_swap_b32_e32 v22, v24
	v_permlane32_swap_b32_e32 v23, v25
	global_store_dwordx4 v[68:69], v[18:21], off offset:128
	global_store_dwordx4 v[68:69], v[22:25], off offset:160
	v_pk_mul_f32 v[2:3], v[66:67], v[2:3] op_sel_hi:[0,1]
	v_pk_mul_f32 v[4:5], v[66:67], v[4:5] op_sel_hi:[0,1]
	v_pk_mul_f32 v[6:7], v[66:67], v[6:7] op_sel_hi:[0,1]
	v_pk_mul_f32 v[8:9], v[66:67], v[8:9] op_sel_hi:[0,1]
	v_pk_mul_f32 v[10:11], v[66:67], v[10:11] op_sel_hi:[0,1]
	v_pk_mul_f32 v[12:13], v[66:67], v[12:13] op_sel_hi:[0,1]
	v_pk_mul_f32 v[14:15], v[66:67], v[14:15] op_sel_hi:[0,1]
	v_pk_mul_f32 v[16:17], v[66:67], v[16:17] op_sel_hi:[0,1]
	v_cvt_pk_bf16_f32 v2, v2, v3
	v_cvt_pk_bf16_f32 v3, v4, v5
	v_cvt_pk_bf16_f32 v4, v6, v7
	v_cvt_pk_bf16_f32 v5, v8, v9
	v_cvt_pk_bf16_f32 v6, v10, v11
	v_cvt_pk_bf16_f32 v7, v12, v13
	v_cvt_pk_bf16_f32 v8, v14, v15
	v_cvt_pk_bf16_f32 v9, v16, v17
	s_nop 1
	v_permlane32_swap_b32_e32 v2, v4
	v_permlane32_swap_b32_e32 v3, v5
	v_permlane32_swap_b32_e32 v6, v8
	v_permlane32_swap_b32_e32 v7, v9
	global_store_dwordx4 v[68:69], v[2:5], off offset:192
	global_store_dwordx4 v[68:69], v[6:9], off offset:224
	s_cmpk_gt_i32 s8, 0x7ff
	s_cbranch_scc1 .LBB0_1519
